# split-K: touch loop prefetches the other slices' partial tiles right after the arrival barrier; on top of the FFO y_old touch stack
# speedup vs baseline: 1.0007x; 1.0007x over previous
.LBB0_1215:
	s_or_b64 exec, exec, s[6:7]
	s_waitcnt lgkmcnt(0)
	s_barrier
	s_mov_b32 s25, 0
.Lspt_rg:
	s_lshr_b32 s0, s84, s25
	s_and_b32 s0, s0, 1
	s_cmp_eq_u32 s0, 0
	s_cbranch_scc1 .Lspt_next
	s_lshr_b32 vcc_lo, s25, 2
	s_and_b32 s0, s25, 3
	s_lshl_b32 vcc_lo, vcc_lo, 13
	s_lshl_b32 s0, s0, 10
	s_add_i32 vcc_lo, vcc_lo, s0
	s_mov_b32 s1, 1
.Lspt_j:
	s_add_i32 s0, s67, s1
	s_cmp_ge_i32 s0, s85
	s_cselect_b32 s0, s85, 0
	s_add_i32 s28, s24, s1
	s_sub_i32 s28, s28, s0
	s_lshl_b32 s28, s28, 17
	s_add_i32 s28, s28, vcc_lo
	s_mov_b32 s29, 0
	v_lshl_add_u64 v[162:163], v[4:5], 0, s[28:29]
	global_load_dword v160, v[162:163], off
	s_add_i32 s28, s28, 0x1000
	s_nop 0
	v_lshl_add_u64 v[162:163], v[4:5], 0, s[28:29]
	global_load_dword v160, v[162:163], off
	s_add_i32 s1, s1, 1
	s_cmp_lt_i32 s1, s85
	s_cbranch_scc1 .Lspt_j
.Lspt_next:
	s_add_i32 s25, s25, 1
	s_cmp_lt_u32 s25, 8
	s_cbranch_scc1 .Lspt_rg
	v_cndmask_b32_e64 v2, 0, 1, s[8:9]
	s_and_b32 s71, s84, 1
	s_and_b32 s63, s84, 2
	s_and_b32 s62, s84, 4
	s_and_b32 s66, s84, 8
	s_and_b32 s65, s84, 16
	s_and_b32 s64, s84, 32
	s_and_b32 s59, s84, 64
	s_and_b32 s58, s84, 0x80
	v_cmp_ne_u32_e64 s[6:7], 1, v2
	s_andn2_b64 vcc, exec, s[8:9]
	s_cbranch_vccnz .LBB0_1224
	s_mov_b32 s1, 1
	s_branch .LBB0_1218
